# P4: g loads nt (streamed once), HL/PP loads plain
# speedup vs baseline: 1.0036x; 1.0036x over previous
; DI void phase_fixup(const Params& p) {
;     ...
;     for (int it = blockIdx.x; it < 512; it += gridDim.x) {
;         const int c = it >> 2, rq = it & 3;
;         float cf[8], cb[8];
;         { const f32x4 a0 = *(const f32x4*)(CAR + (size_t)c * 2048 + ch), a1 = *(const f32x4*)(CAR + (size_t)c * 2048 + ch + 4);
;           const f32x4 b0 = *(const f32x4*)(CAR + (size_t)(128 + c) * 2048 + ch), b1 = *(const f32x4*)(CAR + (size_t)(128 + c) * 2048 + ch + 4);
; #pragma unroll
;           for (int i = 0; i < 4; ++i) { cf[i] = a0[i] * (1.f / 255.f); cf[4 + i] = a1[i] * (1.f / 255.f); cb[i] = b0[i] * (1.f / 255.f); cb[4 + i] = b1[i] * (1.f / 255.f); } }
; #pragma unroll 8
;         for (int i = 0; i < 16; ++i) {
;             const size_t off = (size_t)(c * 128 + rq * 32 + 2 * i + r2) * 2048 + ch;
;             const u32x4 g = __builtin_nontemporal_load((const u32x4*)(ZG + off)), h = __builtin_nontemporal_load((const u32x4*)(HLp + off)), pp = __builtin_nontemporal_load((const u32x4*)(PPp + off));
.LBB0_377:
	s_ashr_i32 s20, s17, 2
	s_ashr_i32 s21, s20, 31
	s_lshl_b64 s[18:19], s[20:21], 13
	v_lshl_add_u64 v[2:3], v[0:1], 0, s[18:19]
	v_add_co_u32_e32 v12, vcc, 0x100000, v2
	global_load_dwordx4 v[14:17], v[2:3], off offset:16
	global_load_dwordx4 v[18:21], v[2:3], off
	v_addc_co_u32_e32 v13, vcc, 0, v3, vcc
	v_lshl_add_u64 v[10:11], v[2:3], 0, s[6:7]
	global_load_dwordx4 v[2:5], v[12:13], off
	global_load_dwordx4 v[6:9], v[10:11], off offset:16
	s_and_b32 s19, s15, 0x60
	v_lshl_or_b32 v26, s20, 7, v50
	s_mov_b32 s18, 0
	v_or_b32_e32 v52, s19, v26
	v_lshl_or_b32 v22, v52, 12, v51
	v_mov_b32_e32 v70, v22
	s_mov_b32 s40, 0xbfb8aa3b
	global_load_dwordx4 v[28:31], v70, s[10:11] nt
	global_load_dwordx4 v[32:35], v70, s[4:5]
	global_load_dwordx4 v[36:39], v70, s[12:13]
	s_waitcnt vmcnt(3)
	v_pk_mul_f32 v[18:19], v[18:19], s[14:15] op_sel_hi:[1,0]
	v_pk_mul_f32 v[20:21], v[20:21], s[14:15] op_sel_hi:[1,0]
	v_pk_mul_f32 v[14:15], v[14:15], s[14:15] op_sel_hi:[1,0]
	v_pk_mul_f32 v[16:17], v[16:17], s[14:15] op_sel_hi:[1,0]
	v_pk_mul_f32 v[2:3], v[2:3], s[14:15] op_sel_hi:[1,0]
	v_pk_mul_f32 v[4:5], v[4:5], s[14:15] op_sel_hi:[1,0]
	v_pk_mul_f32 v[6:7], v[6:7], s[14:15] op_sel_hi:[1,0]
	v_pk_mul_f32 v[8:9], v[8:9], s[14:15] op_sel_hi:[1,0]
	s_waitcnt vmcnt(0)
; DI unsigned cvtpk(float lo, float hi) { unsigned r; asm volatile("v_cvt_pk_bf16_f32 %0, %1, %2" : "=v"(r) : "v"(lo), "v"(hi)); return r; }
; DI float bflo(unsigned w) { return __uint_as_float(w << 16); }
; DI float bfhi(unsigned w) { return __uint_as_float(w & 0xffff0000u); }
; DI float sigm(float x) { return rcpf_(1.f + ex2(-x * LOG2E)); }
; DI float ub(unsigned w, int i) { return (float)((w >> (8 * i)) & 0xffu); }
; DI void phase_fixup(const Params& p) {
;     ...
;         for (int i = 0; i < 16; ++i) {
;             const size_t off = (size_t)(c * 128 + rq * 32 + 2 * i + r2) * 2048 + ch;
;             const u32x4 g = __builtin_nontemporal_load((const u32x4*)(ZG + off)), h = __builtin_nontemporal_load((const u32x4*)(HLp + off)), pp = __builtin_nontemporal_load((const u32x4*)(PPp + off));
;             u32x4 o;
; #pragma unroll
;             for (int k = 0; k < 4; ++k) {
;                 const float g0 = bflo(g[k]), g1 = bfhi(g[k]);
;                 const float y0 = (bflo(h[k]) + ub(pp[k], 0) * cf[2 * k] + ub(pp[k], 1) * cb[2 * k]) * g0 * sigm(g0);
;                 const float y1 = (bfhi(h[k]) + ub(pp[k], 2) * cf[2 * k + 1] + ub(pp[k], 3) * cb[2 * k + 1]) * g1 * sigm(g1);
;                 o[k] = cvtpk(y0, y1);
;             }
;             *(u32x4*)(ZG + off) = o;
;         }
.Lp4_row_loop:
	s_add_i32 s42, s18, 1
	s_min_u32 s42, s42, 15
	s_lshl_b32 s42, s42, 13
	v_add_u32_e32 v71, s42, v22
	global_load_dwordx4 v[54:57], v71, s[10:11] nt
	global_load_dwordx4 v[58:61], v71, s[4:5]
	global_load_dwordx4 v[62:65], v71, s[12:13]
	s_waitcnt vmcnt(4)
	v_lshlrev_b32_e32 v72, 16, v28
	v_and_b32_e32 v73, 0xffff0000, v28
	v_lshlrev_b32_e32 v80, 16, v32
	v_and_b32_e32 v81, 0xffff0000, v32
	v_cvt_f32_ubyte0_e32 v88, v36
	v_cvt_f32_ubyte2_e32 v89, v36
	v_cvt_f32_ubyte1_e32 v96, v36
	v_cvt_f32_ubyte3_e32 v97, v36
	v_lshlrev_b32_e32 v74, 16, v29
	v_and_b32_e32 v75, 0xffff0000, v29
	v_lshlrev_b32_e32 v82, 16, v33
	v_and_b32_e32 v83, 0xffff0000, v33
	v_cvt_f32_ubyte0_e32 v90, v37
	v_cvt_f32_ubyte2_e32 v91, v37
	v_cvt_f32_ubyte1_e32 v98, v37
	v_cvt_f32_ubyte3_e32 v99, v37
	v_lshlrev_b32_e32 v76, 16, v30
	v_and_b32_e32 v77, 0xffff0000, v30
	v_lshlrev_b32_e32 v84, 16, v34
	v_and_b32_e32 v85, 0xffff0000, v34
	v_cvt_f32_ubyte0_e32 v92, v38
	v_cvt_f32_ubyte2_e32 v93, v38
	v_cvt_f32_ubyte1_e32 v100, v38
	v_cvt_f32_ubyte3_e32 v101, v38
	v_lshlrev_b32_e32 v78, 16, v31
	v_and_b32_e32 v79, 0xffff0000, v31
	v_lshlrev_b32_e32 v86, 16, v35
	v_and_b32_e32 v87, 0xffff0000, v35
	v_cvt_f32_ubyte0_e32 v94, v39
	v_cvt_f32_ubyte2_e32 v95, v39
	v_cvt_f32_ubyte1_e32 v102, v39
	v_cvt_f32_ubyte3_e32 v103, v39
	v_pk_mul_f32 v[104:105], v[72:73], s[40:41] op_sel_hi:[1,0]
	v_pk_mul_f32 v[106:107], v[74:75], s[40:41] op_sel_hi:[1,0]
	v_pk_mul_f32 v[108:109], v[76:77], s[40:41] op_sel_hi:[1,0]
	v_pk_mul_f32 v[110:111], v[78:79], s[40:41] op_sel_hi:[1,0]
	v_pk_fma_f32 v[80:81], v[88:89], v[18:19], v[80:81]
	v_pk_fma_f32 v[82:83], v[90:91], v[20:21], v[82:83]
	v_pk_fma_f32 v[84:85], v[92:93], v[14:15], v[84:85]
	v_pk_fma_f32 v[86:87], v[94:95], v[16:17], v[86:87]
	v_exp_f32_e32 v104, v104
	v_exp_f32_e32 v105, v105
	v_exp_f32_e32 v106, v106
	v_exp_f32_e32 v107, v107
	v_exp_f32_e32 v108, v108
	v_exp_f32_e32 v109, v109
	v_exp_f32_e32 v110, v110
	v_exp_f32_e32 v111, v111
	v_pk_fma_f32 v[80:81], v[96:97], v[2:3], v[80:81]
	v_pk_fma_f32 v[82:83], v[98:99], v[4:5], v[82:83]
	v_pk_fma_f32 v[84:85], v[100:101], v[6:7], v[84:85]
	v_pk_fma_f32 v[86:87], v[102:103], v[8:9], v[86:87]
	v_pk_add_f32 v[104:105], v[104:105], 1.0 op_sel_hi:[1,0]
	v_pk_add_f32 v[106:107], v[106:107], 1.0 op_sel_hi:[1,0]
	v_pk_add_f32 v[108:109], v[108:109], 1.0 op_sel_hi:[1,0]
	v_pk_add_f32 v[110:111], v[110:111], 1.0 op_sel_hi:[1,0]
	v_rcp_f32_e32 v104, v104
	v_rcp_f32_e32 v105, v105
	v_rcp_f32_e32 v106, v106
	v_rcp_f32_e32 v107, v107
	v_rcp_f32_e32 v108, v108
	v_rcp_f32_e32 v109, v109
	v_rcp_f32_e32 v110, v110
	v_rcp_f32_e32 v111, v111
	v_pk_mul_f32 v[80:81], v[80:81], v[72:73]
	v_pk_mul_f32 v[82:83], v[82:83], v[74:75]
	v_pk_mul_f32 v[84:85], v[84:85], v[76:77]
	v_pk_mul_f32 v[86:87], v[86:87], v[78:79]
	v_pk_mul_f32 v[80:81], v[104:105], v[80:81]
	v_pk_mul_f32 v[82:83], v[106:107], v[82:83]
	v_pk_mul_f32 v[84:85], v[108:109], v[84:85]
	v_pk_mul_f32 v[86:87], v[110:111], v[86:87]
	v_cvt_pk_bf16_f32 v24, v80, v81
	v_cvt_pk_bf16_f32 v25, v82, v83
	v_cvt_pk_bf16_f32 v26, v84, v85
	v_cvt_pk_bf16_f32 v27, v86, v87
	global_store_dwordx4 v70, v[24:27], s[10:11]
	s_add_i32 s42, s18, 2
	s_min_u32 s42, s42, 15
	s_lshl_b32 s42, s42, 13
	v_add_u32_e32 v70, s42, v22
	global_load_dwordx4 v[28:31], v70, s[10:11] nt
	global_load_dwordx4 v[32:35], v70, s[4:5]
	global_load_dwordx4 v[36:39], v70, s[12:13]
	s_waitcnt vmcnt(4)
	v_lshlrev_b32_e32 v72, 16, v54
	v_and_b32_e32 v73, 0xffff0000, v54
	v_lshlrev_b32_e32 v80, 16, v58
	v_and_b32_e32 v81, 0xffff0000, v58
	v_cvt_f32_ubyte0_e32 v88, v62
	v_cvt_f32_ubyte2_e32 v89, v62
	v_cvt_f32_ubyte1_e32 v96, v62
	v_cvt_f32_ubyte3_e32 v97, v62
	v_lshlrev_b32_e32 v74, 16, v55
	v_and_b32_e32 v75, 0xffff0000, v55
	v_lshlrev_b32_e32 v82, 16, v59
	v_and_b32_e32 v83, 0xffff0000, v59
	v_cvt_f32_ubyte0_e32 v90, v63
	v_cvt_f32_ubyte2_e32 v91, v63
	v_cvt_f32_ubyte1_e32 v98, v63
	v_cvt_f32_ubyte3_e32 v99, v63
	v_lshlrev_b32_e32 v76, 16, v56
	v_and_b32_e32 v77, 0xffff0000, v56
	v_lshlrev_b32_e32 v84, 16, v60
	v_and_b32_e32 v85, 0xffff0000, v60
	v_cvt_f32_ubyte0_e32 v92, v64
	v_cvt_f32_ubyte2_e32 v93, v64
	v_cvt_f32_ubyte1_e32 v100, v64
	v_cvt_f32_ubyte3_e32 v101, v64
	v_lshlrev_b32_e32 v78, 16, v57
	v_and_b32_e32 v79, 0xffff0000, v57
	v_lshlrev_b32_e32 v86, 16, v61
	v_and_b32_e32 v87, 0xffff0000, v61
	v_cvt_f32_ubyte0_e32 v94, v65
	v_cvt_f32_ubyte2_e32 v95, v65
	v_cvt_f32_ubyte1_e32 v102, v65
	v_cvt_f32_ubyte3_e32 v103, v65
	v_pk_mul_f32 v[104:105], v[72:73], s[40:41] op_sel_hi:[1,0]
	v_pk_mul_f32 v[106:107], v[74:75], s[40:41] op_sel_hi:[1,0]
	v_pk_mul_f32 v[108:109], v[76:77], s[40:41] op_sel_hi:[1,0]
	v_pk_mul_f32 v[110:111], v[78:79], s[40:41] op_sel_hi:[1,0]
	v_pk_fma_f32 v[80:81], v[88:89], v[18:19], v[80:81]
	v_pk_fma_f32 v[82:83], v[90:91], v[20:21], v[82:83]
	v_pk_fma_f32 v[84:85], v[92:93], v[14:15], v[84:85]
	v_pk_fma_f32 v[86:87], v[94:95], v[16:17], v[86:87]
	v_exp_f32_e32 v104, v104
	v_exp_f32_e32 v105, v105
	v_exp_f32_e32 v106, v106
	v_exp_f32_e32 v107, v107
	v_exp_f32_e32 v108, v108
	v_exp_f32_e32 v109, v109
	v_exp_f32_e32 v110, v110
	v_exp_f32_e32 v111, v111
	v_pk_fma_f32 v[80:81], v[96:97], v[2:3], v[80:81]
	v_pk_fma_f32 v[82:83], v[98:99], v[4:5], v[82:83]
	v_pk_fma_f32 v[84:85], v[100:101], v[6:7], v[84:85]
	v_pk_fma_f32 v[86:87], v[102:103], v[8:9], v[86:87]
	v_pk_add_f32 v[104:105], v[104:105], 1.0 op_sel_hi:[1,0]
	v_pk_add_f32 v[106:107], v[106:107], 1.0 op_sel_hi:[1,0]
	v_pk_add_f32 v[108:109], v[108:109], 1.0 op_sel_hi:[1,0]
	v_pk_add_f32 v[110:111], v[110:111], 1.0 op_sel_hi:[1,0]
	v_rcp_f32_e32 v104, v104
	v_rcp_f32_e32 v105, v105
	v_rcp_f32_e32 v106, v106
	v_rcp_f32_e32 v107, v107
	v_rcp_f32_e32 v108, v108
	v_rcp_f32_e32 v109, v109
	v_rcp_f32_e32 v110, v110
	v_rcp_f32_e32 v111, v111
	v_pk_mul_f32 v[80:81], v[80:81], v[72:73]
	v_pk_mul_f32 v[82:83], v[82:83], v[74:75]
	v_pk_mul_f32 v[84:85], v[84:85], v[76:77]
	v_pk_mul_f32 v[86:87], v[86:87], v[78:79]
	v_pk_mul_f32 v[80:81], v[104:105], v[80:81]
	v_pk_mul_f32 v[82:83], v[106:107], v[82:83]
	v_pk_mul_f32 v[84:85], v[108:109], v[84:85]
	v_pk_mul_f32 v[86:87], v[110:111], v[86:87]
	v_cvt_pk_bf16_f32 v66, v80, v81
	v_cvt_pk_bf16_f32 v67, v82, v83
	v_cvt_pk_bf16_f32 v68, v84, v85
	v_cvt_pk_bf16_f32 v69, v86, v87
	global_store_dwordx4 v71, v[66:69], s[10:11]
	s_add_i32 s18, s18, 2
	s_cmp_lt_u32 s18, 16
	s_cbranch_scc1 .Lp4_row_loop
	s_add_i32 s17, s17, s24
	s_add_i32 s15, s15, s16
	s_cmpk_gt_i32 s17, 0x1ff
	s_cbranch_scc0 .LBB0_377
	s_load_dwordx2 s[4:5], s[0:1], 0xc8
	s_waitcnt lgkmcnt(0)
	v_mov_b64_e32 v[0:1], s[4:5]
